# scan step loops: wider lgkmcnt coalescing (window 6) on top of rolling prefetch + hoisted constants + idle secondary + mod_unit rewrites
# baseline (speedup 1.0000x reference)
.LBB0_459:
	v_add_u32_e32 v137, s14, v201
	v_add_u32_e32 v136, s14, v205
	v_pk_mul_f32 v[134:135], v[104:105], v[84:85]
	v_pk_mul_f32 v[104:105], v[104:105], v[76:77]
	v_pk_fma_f32 v[134:135], v[86:87], v[106:107], v[134:135]
	v_pk_fma_f32 v[104:105], v[78:79], v[106:107], v[104:105]
	v_pk_fma_f32 v[134:135], v[80:81], v[112:113], v[134:135]
	v_pk_fma_f32 v[104:105], v[72:73], v[112:113], v[104:105]
	v_pk_fma_f32 v[134:135], v[82:83], v[114:115], v[134:135]
	v_pk_fma_f32 v[138:139], v[74:75], v[114:115], v[104:105]
	ds_read_b128 v[104:107], v137 offset:33024
	ds_read_b128 v[112:115], v137 offset:33040
	v_add_f32_e32 v134, v134, v135
	v_add_f32_e32 v135, v138, v139
	v_pk_mul_f32 v[140:141], v[88:89], v[130:131] op_sel_hi:[1,0]
	v_add_f32_dpp v134, v134, v134 quad_perm:[1,0,3,2] row_mask:0xf bank_mask:0xf bound_ctrl:1
	v_add_f32_dpp v135, v135, v135 quad_perm:[1,0,3,2] row_mask:0xf bank_mask:0xf bound_ctrl:1
	v_pk_mul_f32 v[142:143], v[90:91], v[130:131] op_sel_hi:[1,0]
	v_add_f32_dpp v134, v134, v134 quad_perm:[2,3,0,1] row_mask:0xf bank_mask:0xf bound_ctrl:1
	v_add_f32_dpp v135, v135, v135 quad_perm:[2,3,0,1] row_mask:0xf bank_mask:0xf bound_ctrl:1
	v_pk_mul_f32 v[144:145], v[96:97], v[130:131] op_sel_hi:[1,0]
	v_pk_mul_f32 v[146:147], v[98:99], v[130:131] op_sel_hi:[1,0]
	v_pk_mul_f32 v[164:165], v[88:89], v[132:133] op_sel_hi:[1,0]
	v_add_f32_dpp v134, v134, v134 row_half_mirror row_mask:0xf bank_mask:0xf bound_ctrl:1
	v_add_f32_dpp v138, v135, v135 row_half_mirror row_mask:0xf bank_mask:0xf bound_ctrl:1
	v_pk_mul_f32 v[166:167], v[90:91], v[132:133] op_sel_hi:[1,0]
	v_pk_mul_f32 v[168:169], v[96:97], v[132:133] op_sel_hi:[1,0]
	v_pk_mul_f32 v[132:133], v[98:99], v[132:133] op_sel_hi:[1,0]
	ds_read_b128 v[96:99], v137 offset:8448
	ds_read_b128 v[88:91], v137 offset:8464
	ds_read2_b32 v[130:131], v136 offset1:32
	s_waitcnt lgkmcnt(11)
	v_pk_fma_f32 v[140:141], v[134:135], v[92:93], v[140:141] op_sel_hi:[0,1,1]
	v_pk_fma_f32 v[142:143], v[134:135], v[94:95], v[142:143] op_sel_hi:[0,1,1]
	v_pk_fma_f32 v[144:145], v[134:135], v[100:101], v[144:145] op_sel_hi:[0,1,1]
	v_pk_fma_f32 v[134:135], v[134:135], v[102:103], v[146:147] op_sel_hi:[0,1,1]
	v_pk_fma_f32 v[146:147], v[138:139], v[92:93], v[164:165] op_sel_hi:[0,1,1]
	v_pk_fma_f32 v[164:165], v[138:139], v[94:95], v[166:167] op_sel_hi:[0,1,1]
	v_pk_fma_f32 v[132:133], v[138:139], v[102:103], v[132:133] op_sel_hi:[0,1,1]
	s_waitcnt lgkmcnt(10)
	v_pk_fma_f32 v[84:85], v[84:85], v[108:109], v[140:141]
	v_pk_fma_f32 v[108:109], v[76:77], v[108:109], v[146:147]
	v_pk_fma_f32 v[166:167], v[138:139], v[100:101], v[168:169] op_sel_hi:[0,1,1]
	ds_read_b128 v[100:103], v137 offset:41216
	ds_read_b128 v[92:95], v137 offset:41232
	v_pk_fma_f32 v[86:87], v[86:87], v[110:111], v[142:143]
	s_waitcnt lgkmcnt(10)
	v_pk_fma_f32 v[82:83], v[82:83], v[118:119], v[134:135]
	v_pk_fma_f32 v[110:111], v[78:79], v[110:111], v[164:165]
	v_pk_fma_f32 v[118:119], v[74:75], v[118:119], v[132:133]
	v_pk_mul_f32 v[132:133], v[120:121], v[84:85]
	v_pk_mul_f32 v[120:121], v[120:121], v[108:109]
	v_pk_fma_f32 v[80:81], v[80:81], v[116:117], v[144:145]
	v_pk_fma_f32 v[116:117], v[72:73], v[116:117], v[166:167]
	v_pk_fma_f32 v[132:133], v[86:87], v[122:123], v[132:133]
	v_pk_fma_f32 v[120:121], v[110:111], v[122:123], v[120:121]
	s_waitcnt lgkmcnt(9)
	v_pk_fma_f32 v[132:133], v[80:81], v[124:125], v[132:133]
	v_pk_fma_f32 v[120:121], v[116:117], v[124:125], v[120:121]
	v_pk_fma_f32 v[132:133], v[82:83], v[126:127], v[132:133]
	v_pk_fma_f32 v[134:135], v[118:119], v[126:127], v[120:121]
	v_add_f32_e32 v132, v132, v133
	v_add_f32_e32 v133, v134, v135
	ds_read_b128 v[76:79], v137 offset:24832
	v_add_f32_dpp v132, v132, v132 quad_perm:[1,0,3,2] row_mask:0xf bank_mask:0xf bound_ctrl:1
	v_add_f32_dpp v133, v133, v133 quad_perm:[1,0,3,2] row_mask:0xf bank_mask:0xf bound_ctrl:1
	ds_read_b128 v[72:75], v137 offset:24848
	v_add_f32_dpp v132, v132, v132 quad_perm:[2,3,0,1] row_mask:0xf bank_mask:0xf bound_ctrl:1
	v_add_f32_dpp v133, v133, v133 quad_perm:[2,3,0,1] row_mask:0xf bank_mask:0xf bound_ctrl:1
	ds_read_b128 v[124:127], v137 offset:256
	v_add_f32_dpp v132, v132, v132 row_half_mirror row_mask:0xf bank_mask:0xf bound_ctrl:1
	v_add_f32_dpp v133, v133, v133 row_half_mirror row_mask:0xf bank_mask:0xf bound_ctrl:1
	ds_read_b128 v[120:123], v137 offset:272
	ds_write_b32 v136, v132 offset:32512
	ds_write_b32 v136, v133 offset:32640
	s_waitcnt lgkmcnt(11)
	v_pk_mul_f32 v[132:133], v[104:105], v[84:85]
	v_pk_mul_f32 v[104:105], v[104:105], v[108:109]
	v_pk_fma_f32 v[132:133], v[86:87], v[106:107], v[132:133]
	v_pk_fma_f32 v[104:105], v[110:111], v[106:107], v[104:105]
	v_pk_fma_f32 v[132:133], v[80:81], v[112:113], v[132:133]
	v_pk_fma_f32 v[104:105], v[116:117], v[112:113], v[104:105]
	v_pk_fma_f32 v[132:133], v[82:83], v[114:115], v[132:133]
	v_pk_fma_f32 v[134:135], v[118:119], v[114:115], v[104:105]
	ds_read_b128 v[104:107], v137 offset:33280
	ds_read_b128 v[112:115], v137 offset:33296
	v_add_f32_e32 v132, v132, v133
	v_add_f32_e32 v133, v134, v135
	s_waitcnt lgkmcnt(10)
	v_pk_mul_f32 v[138:139], v[96:97], v[130:131] op_sel_hi:[1,0]
	v_add_f32_dpp v132, v132, v132 quad_perm:[1,0,3,2] row_mask:0xf bank_mask:0xf bound_ctrl:1
	v_add_f32_dpp v133, v133, v133 quad_perm:[1,0,3,2] row_mask:0xf bank_mask:0xf bound_ctrl:1
	v_pk_mul_f32 v[140:141], v[98:99], v[130:131] op_sel_hi:[1,0]
	v_pk_mul_f32 v[142:143], v[88:89], v[130:131] op_sel_hi:[1,0]
	v_pk_mul_f32 v[144:145], v[90:91], v[130:131] op_sel_hi:[1,0]
	v_mov_b32_e32 v130, v131
	v_add_f32_dpp v132, v132, v132 quad_perm:[2,3,0,1] row_mask:0xf bank_mask:0xf bound_ctrl:1
	v_add_f32_dpp v133, v133, v133 quad_perm:[2,3,0,1] row_mask:0xf bank_mask:0xf bound_ctrl:1
	v_pk_mul_f32 v[146:147], v[96:97], v[130:131] op_sel_hi:[1,0]
	v_add_f32_dpp v132, v132, v132 row_half_mirror row_mask:0xf bank_mask:0xf bound_ctrl:1
	v_add_f32_dpp v134, v133, v133 row_half_mirror row_mask:0xf bank_mask:0xf bound_ctrl:1
	v_pk_mul_f32 v[164:165], v[98:99], v[130:131] op_sel_hi:[1,0]
	s_waitcnt lgkmcnt(8)
	v_pk_fma_f32 v[138:139], v[132:133], v[100:101], v[138:139] op_sel_hi:[0,1,1]
	v_pk_fma_f32 v[140:141], v[132:133], v[102:103], v[140:141] op_sel_hi:[0,1,1]
	v_pk_fma_f32 v[142:143], v[132:133], v[92:93], v[142:143] op_sel_hi:[0,1,1]
	v_pk_fma_f32 v[132:133], v[132:133], v[94:95], v[144:145] op_sel_hi:[0,1,1]
	v_pk_fma_f32 v[144:145], v[134:135], v[100:101], v[146:147] op_sel_hi:[0,1,1]
	v_pk_mul_f32 v[166:167], v[88:89], v[130:131] op_sel_hi:[1,0]
	v_pk_fma_f32 v[146:147], v[134:135], v[102:103], v[164:165] op_sel_hi:[0,1,1]
	s_waitcnt lgkmcnt(7)
	v_pk_fma_f32 v[84:85], v[84:85], v[76:77], v[138:139]
	v_pk_fma_f32 v[76:77], v[108:109], v[76:77], v[144:145]
	v_pk_mul_f32 v[168:169], v[90:91], v[130:131] op_sel_hi:[1,0]
	ds_read_b128 v[88:91], v137 offset:8704
	ds_read_b128 v[96:99], v137 offset:8720
	ds_read2_b32 v[130:131], v136 offset0:64 offset1:96
	v_pk_fma_f32 v[164:165], v[134:135], v[92:93], v[166:167] op_sel_hi:[0,1,1]
	v_pk_fma_f32 v[86:87], v[86:87], v[78:79], v[140:141]
	s_waitcnt lgkmcnt(8)
	v_pk_fma_f32 v[82:83], v[82:83], v[74:75], v[132:133]
	v_pk_fma_f32 v[78:79], v[110:111], v[78:79], v[146:147]
	v_pk_mul_f32 v[132:133], v[124:125], v[84:85]
	v_pk_mul_f32 v[124:125], v[124:125], v[76:77]
	v_pk_fma_f32 v[134:135], v[134:135], v[94:95], v[168:169] op_sel_hi:[0,1,1]
	ds_read_b128 v[92:95], v137 offset:41472
	ds_read_b128 v[100:103], v137 offset:41488
	v_pk_fma_f32 v[80:81], v[80:81], v[72:73], v[142:143]
	v_pk_fma_f32 v[72:73], v[116:117], v[72:73], v[164:165]
	v_pk_fma_f32 v[132:133], v[86:87], v[126:127], v[132:133]
	v_pk_fma_f32 v[124:125], v[78:79], v[126:127], v[124:125]
	v_pk_fma_f32 v[74:75], v[118:119], v[74:75], v[134:135]
	s_waitcnt lgkmcnt(9)
	v_pk_fma_f32 v[132:133], v[80:81], v[120:121], v[132:133]
	v_pk_fma_f32 v[120:121], v[72:73], v[120:121], v[124:125]
	v_pk_fma_f32 v[132:133], v[82:83], v[122:123], v[132:133]
	v_pk_fma_f32 v[134:135], v[74:75], v[122:123], v[120:121]
	v_add_f32_e32 v132, v132, v133
	v_add_f32_e32 v133, v134, v135
	ds_read_b128 v[108:111], v137 offset:25088
	v_add_f32_dpp v132, v132, v132 quad_perm:[1,0,3,2] row_mask:0xf bank_mask:0xf bound_ctrl:1
	v_add_f32_dpp v133, v133, v133 quad_perm:[1,0,3,2] row_mask:0xf bank_mask:0xf bound_ctrl:1
	ds_read_b128 v[116:119], v137 offset:25104
	v_add_f32_dpp v132, v132, v132 quad_perm:[2,3,0,1] row_mask:0xf bank_mask:0xf bound_ctrl:1
	v_add_f32_dpp v133, v133, v133 quad_perm:[2,3,0,1] row_mask:0xf bank_mask:0xf bound_ctrl:1
	ds_read_b128 v[120:123], v137 offset:512
	v_add_f32_dpp v132, v132, v132 row_half_mirror row_mask:0xf bank_mask:0xf bound_ctrl:1
	v_add_f32_dpp v133, v133, v133 row_half_mirror row_mask:0xf bank_mask:0xf bound_ctrl:1
	ds_read_b128 v[124:127], v137 offset:528
	ds_write_b32 v136, v132 offset:32768
	ds_write_b32 v136, v133 offset:32896
	s_waitcnt lgkmcnt(8)
	v_mov_b32_e32 v132, v131
	s_addk_i32 s14, 0x200
	s_cmpk_eq_i32 s14, 0x2000
	s_cbranch_scc0 .LBB0_459
	s_waitcnt lgkmcnt(0)
	s_barrier
	ds_read_b128 v[88:91], v199 offset:49152
	ds_read_b128 v[92:95], v199 offset:49168
	s_cmp_eq_u32 s2, 8
	s_waitcnt lgkmcnt(1)
	v_cvt_pk_bf16_f32 v88, v88, v89
	v_cvt_pk_bf16_f32 v89, v90, v91
	s_waitcnt lgkmcnt(0)
	v_cvt_pk_bf16_f32 v90, v92, v93
	v_lshlrev_b64 v[92:93], 10, v[128:129]
	v_cvt_pk_bf16_f32 v91, v94, v95
	v_lshl_add_u64 v[92:93], v[154:155], 0, v[92:93]
	global_store_dwordx4 v[92:93], v[88:91], off
	s_cbranch_scc1 .LBB0_463
	v_mov_b64_e32 v[106:107], v[70:71]
	v_mov_b64_e32 v[90:91], v[54:55]
	v_mov_b64_e32 v[94:95], v[58:59]
	v_mov_b64_e32 v[110:111], v[62:63]
	v_mov_b64_e32 v[114:115], v[66:67]
	v_mov_b64_e32 v[104:105], v[68:69]
	v_mov_b64_e32 v[88:89], v[52:53]
	v_mov_b64_e32 v[92:93], v[56:57]
	v_mov_b64_e32 v[108:109], v[60:61]
	v_mov_b64_e32 v[112:113], v[64:65]
	s_mov_b32 s14, s2
	s_branch .LBB0_447

.LBB0_493:
	v_add_u32_e32 v137, s14, v197
	v_add_u32_e32 v136, s14, v148
	v_pk_mul_f32 v[134:135], v[104:105], v[36:37]
	v_pk_mul_f32 v[104:105], v[104:105], v[40:41]
	v_pk_fma_f32 v[134:135], v[38:39], v[106:107], v[134:135]
	v_pk_fma_f32 v[104:105], v[42:43], v[106:107], v[104:105]
	v_pk_fma_f32 v[134:135], v[32:33], v[112:113], v[134:135]
	v_pk_fma_f32 v[104:105], v[44:45], v[112:113], v[104:105]
	v_pk_fma_f32 v[134:135], v[34:35], v[114:115], v[134:135]
	v_pk_fma_f32 v[138:139], v[46:47], v[114:115], v[104:105]
	ds_read_b128 v[104:107], v137 offset:33024
	ds_read_b128 v[112:115], v137 offset:33040
	v_add_f32_e32 v134, v134, v135
	v_add_f32_e32 v135, v138, v139
	v_pk_mul_f32 v[140:141], v[88:89], v[130:131] op_sel_hi:[1,0]
	v_add_f32_dpp v134, v134, v134 quad_perm:[1,0,3,2] row_mask:0xf bank_mask:0xf bound_ctrl:1
	v_add_f32_dpp v135, v135, v135 quad_perm:[1,0,3,2] row_mask:0xf bank_mask:0xf bound_ctrl:1
	v_pk_mul_f32 v[142:143], v[90:91], v[130:131] op_sel_hi:[1,0]
	v_add_f32_dpp v134, v134, v134 quad_perm:[2,3,0,1] row_mask:0xf bank_mask:0xf bound_ctrl:1
	v_add_f32_dpp v135, v135, v135 quad_perm:[2,3,0,1] row_mask:0xf bank_mask:0xf bound_ctrl:1
	v_pk_mul_f32 v[144:145], v[96:97], v[130:131] op_sel_hi:[1,0]
	v_pk_mul_f32 v[146:147], v[98:99], v[130:131] op_sel_hi:[1,0]
	v_pk_mul_f32 v[160:161], v[88:89], v[132:133] op_sel_hi:[1,0]
	v_add_f32_dpp v134, v134, v134 row_half_mirror row_mask:0xf bank_mask:0xf bound_ctrl:1
	v_add_f32_dpp v138, v135, v135 row_half_mirror row_mask:0xf bank_mask:0xf bound_ctrl:1
	v_pk_mul_f32 v[162:163], v[90:91], v[132:133] op_sel_hi:[1,0]
	v_pk_mul_f32 v[164:165], v[96:97], v[132:133] op_sel_hi:[1,0]
	v_pk_mul_f32 v[132:133], v[98:99], v[132:133] op_sel_hi:[1,0]
	ds_read_b128 v[96:99], v137 offset:8448
	ds_read_b128 v[88:91], v137 offset:8464
	ds_read2_b32 v[130:131], v136 offset1:32
	s_waitcnt lgkmcnt(11)
	v_pk_fma_f32 v[140:141], v[134:135], v[92:93], v[140:141] op_sel_hi:[0,1,1]
	v_pk_fma_f32 v[142:143], v[134:135], v[94:95], v[142:143] op_sel_hi:[0,1,1]
	v_pk_fma_f32 v[144:145], v[134:135], v[100:101], v[144:145] op_sel_hi:[0,1,1]
	v_pk_fma_f32 v[134:135], v[134:135], v[102:103], v[146:147] op_sel_hi:[0,1,1]
	v_pk_fma_f32 v[146:147], v[138:139], v[92:93], v[160:161] op_sel_hi:[0,1,1]
	v_pk_fma_f32 v[160:161], v[138:139], v[94:95], v[162:163] op_sel_hi:[0,1,1]
	v_pk_fma_f32 v[132:133], v[138:139], v[102:103], v[132:133] op_sel_hi:[0,1,1]
	s_waitcnt lgkmcnt(10)
	v_pk_fma_f32 v[36:37], v[36:37], v[108:109], v[140:141]
	v_pk_fma_f32 v[108:109], v[40:41], v[108:109], v[146:147]
	v_pk_fma_f32 v[162:163], v[138:139], v[100:101], v[164:165] op_sel_hi:[0,1,1]
	ds_read_b128 v[100:103], v137 offset:41216
	ds_read_b128 v[92:95], v137 offset:41232
	v_pk_fma_f32 v[38:39], v[38:39], v[110:111], v[142:143]
	s_waitcnt lgkmcnt(10)
	v_pk_fma_f32 v[34:35], v[34:35], v[118:119], v[134:135]
	v_pk_fma_f32 v[110:111], v[42:43], v[110:111], v[160:161]
	v_pk_fma_f32 v[118:119], v[46:47], v[118:119], v[132:133]
	v_pk_mul_f32 v[132:133], v[120:121], v[36:37]
	v_pk_mul_f32 v[120:121], v[120:121], v[108:109]
	v_pk_fma_f32 v[32:33], v[32:33], v[116:117], v[144:145]
	v_pk_fma_f32 v[116:117], v[44:45], v[116:117], v[162:163]
	v_pk_fma_f32 v[132:133], v[38:39], v[122:123], v[132:133]
	v_pk_fma_f32 v[120:121], v[110:111], v[122:123], v[120:121]
	s_waitcnt lgkmcnt(9)
	v_pk_fma_f32 v[132:133], v[32:33], v[124:125], v[132:133]
	v_pk_fma_f32 v[120:121], v[116:117], v[124:125], v[120:121]
	v_pk_fma_f32 v[132:133], v[34:35], v[126:127], v[132:133]
	v_pk_fma_f32 v[134:135], v[118:119], v[126:127], v[120:121]
	v_add_f32_e32 v132, v132, v133
	v_add_f32_e32 v133, v134, v135
	ds_read_b128 v[40:43], v137 offset:24832
	v_add_f32_dpp v132, v132, v132 quad_perm:[1,0,3,2] row_mask:0xf bank_mask:0xf bound_ctrl:1
	v_add_f32_dpp v133, v133, v133 quad_perm:[1,0,3,2] row_mask:0xf bank_mask:0xf bound_ctrl:1
	ds_read_b128 v[44:47], v137 offset:24848
	v_add_f32_dpp v132, v132, v132 quad_perm:[2,3,0,1] row_mask:0xf bank_mask:0xf bound_ctrl:1
	v_add_f32_dpp v133, v133, v133 quad_perm:[2,3,0,1] row_mask:0xf bank_mask:0xf bound_ctrl:1
	ds_read_b128 v[124:127], v137 offset:256
	v_add_f32_dpp v132, v132, v132 row_half_mirror row_mask:0xf bank_mask:0xf bound_ctrl:1
	v_add_f32_dpp v133, v133, v133 row_half_mirror row_mask:0xf bank_mask:0xf bound_ctrl:1
	ds_read_b128 v[120:123], v137 offset:272
	ds_write_b32 v136, v132 offset:32512
	ds_write_b32 v136, v133 offset:32640
	s_waitcnt lgkmcnt(11)
	v_pk_mul_f32 v[132:133], v[104:105], v[36:37]
	v_pk_mul_f32 v[104:105], v[104:105], v[108:109]
	v_pk_fma_f32 v[132:133], v[38:39], v[106:107], v[132:133]
	v_pk_fma_f32 v[104:105], v[110:111], v[106:107], v[104:105]
	v_pk_fma_f32 v[132:133], v[32:33], v[112:113], v[132:133]
	v_pk_fma_f32 v[104:105], v[116:117], v[112:113], v[104:105]
	v_pk_fma_f32 v[132:133], v[34:35], v[114:115], v[132:133]
	v_pk_fma_f32 v[134:135], v[118:119], v[114:115], v[104:105]
	ds_read_b128 v[104:107], v137 offset:33280
	ds_read_b128 v[112:115], v137 offset:33296
	v_add_f32_e32 v132, v132, v133
	v_add_f32_e32 v133, v134, v135
	s_waitcnt lgkmcnt(10)
	v_pk_mul_f32 v[138:139], v[96:97], v[130:131] op_sel_hi:[1,0]
	v_add_f32_dpp v132, v132, v132 quad_perm:[1,0,3,2] row_mask:0xf bank_mask:0xf bound_ctrl:1
	v_add_f32_dpp v133, v133, v133 quad_perm:[1,0,3,2] row_mask:0xf bank_mask:0xf bound_ctrl:1
	v_pk_mul_f32 v[140:141], v[98:99], v[130:131] op_sel_hi:[1,0]
	v_pk_mul_f32 v[142:143], v[88:89], v[130:131] op_sel_hi:[1,0]
	v_pk_mul_f32 v[144:145], v[90:91], v[130:131] op_sel_hi:[1,0]
	v_mov_b32_e32 v130, v131
	v_add_f32_dpp v132, v132, v132 quad_perm:[2,3,0,1] row_mask:0xf bank_mask:0xf bound_ctrl:1
	v_add_f32_dpp v133, v133, v133 quad_perm:[2,3,0,1] row_mask:0xf bank_mask:0xf bound_ctrl:1
	v_pk_mul_f32 v[146:147], v[96:97], v[130:131] op_sel_hi:[1,0]
	v_add_f32_dpp v132, v132, v132 row_half_mirror row_mask:0xf bank_mask:0xf bound_ctrl:1
	v_add_f32_dpp v134, v133, v133 row_half_mirror row_mask:0xf bank_mask:0xf bound_ctrl:1
	v_pk_mul_f32 v[160:161], v[98:99], v[130:131] op_sel_hi:[1,0]
	s_waitcnt lgkmcnt(8)
	v_pk_fma_f32 v[138:139], v[132:133], v[100:101], v[138:139] op_sel_hi:[0,1,1]
	v_pk_fma_f32 v[140:141], v[132:133], v[102:103], v[140:141] op_sel_hi:[0,1,1]
	v_pk_fma_f32 v[142:143], v[132:133], v[92:93], v[142:143] op_sel_hi:[0,1,1]
	v_pk_fma_f32 v[132:133], v[132:133], v[94:95], v[144:145] op_sel_hi:[0,1,1]
	v_pk_fma_f32 v[144:145], v[134:135], v[100:101], v[146:147] op_sel_hi:[0,1,1]
	v_pk_mul_f32 v[162:163], v[88:89], v[130:131] op_sel_hi:[1,0]
	v_pk_fma_f32 v[146:147], v[134:135], v[102:103], v[160:161] op_sel_hi:[0,1,1]
	s_waitcnt lgkmcnt(7)
	v_pk_fma_f32 v[36:37], v[36:37], v[40:41], v[138:139]
	v_pk_fma_f32 v[40:41], v[108:109], v[40:41], v[144:145]
	v_pk_mul_f32 v[164:165], v[90:91], v[130:131] op_sel_hi:[1,0]
	ds_read_b128 v[88:91], v137 offset:8704
	ds_read_b128 v[96:99], v137 offset:8720
	ds_read2_b32 v[130:131], v136 offset0:64 offset1:96
	v_pk_fma_f32 v[160:161], v[134:135], v[92:93], v[162:163] op_sel_hi:[0,1,1]
	v_pk_fma_f32 v[38:39], v[38:39], v[42:43], v[140:141]
	s_waitcnt lgkmcnt(8)
	v_pk_fma_f32 v[34:35], v[34:35], v[46:47], v[132:133]
	v_pk_fma_f32 v[42:43], v[110:111], v[42:43], v[146:147]
	v_pk_mul_f32 v[132:133], v[124:125], v[36:37]
	v_pk_mul_f32 v[124:125], v[124:125], v[40:41]
	v_pk_fma_f32 v[134:135], v[134:135], v[94:95], v[164:165] op_sel_hi:[0,1,1]
	ds_read_b128 v[92:95], v137 offset:41472
	ds_read_b128 v[100:103], v137 offset:41488
	v_pk_fma_f32 v[32:33], v[32:33], v[44:45], v[142:143]
	v_pk_fma_f32 v[44:45], v[116:117], v[44:45], v[160:161]
	v_pk_fma_f32 v[132:133], v[38:39], v[126:127], v[132:133]
	v_pk_fma_f32 v[124:125], v[42:43], v[126:127], v[124:125]
	v_pk_fma_f32 v[46:47], v[118:119], v[46:47], v[134:135]
	s_waitcnt lgkmcnt(9)
	v_pk_fma_f32 v[132:133], v[32:33], v[120:121], v[132:133]
	v_pk_fma_f32 v[120:121], v[44:45], v[120:121], v[124:125]
	v_pk_fma_f32 v[132:133], v[34:35], v[122:123], v[132:133]
	v_pk_fma_f32 v[134:135], v[46:47], v[122:123], v[120:121]
	v_add_f32_e32 v132, v132, v133
	v_add_f32_e32 v133, v134, v135
	ds_read_b128 v[108:111], v137 offset:25088
	v_add_f32_dpp v132, v132, v132 quad_perm:[1,0,3,2] row_mask:0xf bank_mask:0xf bound_ctrl:1
	v_add_f32_dpp v133, v133, v133 quad_perm:[1,0,3,2] row_mask:0xf bank_mask:0xf bound_ctrl:1
	ds_read_b128 v[116:119], v137 offset:25104
	v_add_f32_dpp v132, v132, v132 quad_perm:[2,3,0,1] row_mask:0xf bank_mask:0xf bound_ctrl:1
	v_add_f32_dpp v133, v133, v133 quad_perm:[2,3,0,1] row_mask:0xf bank_mask:0xf bound_ctrl:1
	ds_read_b128 v[120:123], v137 offset:512
	v_add_f32_dpp v132, v132, v132 row_half_mirror row_mask:0xf bank_mask:0xf bound_ctrl:1
	v_add_f32_dpp v133, v133, v133 row_half_mirror row_mask:0xf bank_mask:0xf bound_ctrl:1
	ds_read_b128 v[124:127], v137 offset:528
	ds_write_b32 v136, v132 offset:32768
	ds_write_b32 v136, v133 offset:32896
	s_waitcnt lgkmcnt(8)
	v_mov_b32_e32 v132, v131
	s_addk_i32 s14, 0x200
	s_cmpk_eq_i32 s14, 0x2000
	s_cbranch_scc0 .LBB0_493
	s_waitcnt lgkmcnt(0)
	s_barrier
	ds_read_b128 v[88:91], v195 offset:49152
	ds_read_b128 v[92:95], v195 offset:49168
	v_mov_b64_e32 v[106:107], v[86:87]
	v_mov_b64_e32 v[98:99], v[74:75]
	v_mov_b64_e32 v[110:111], v[78:79]
	s_waitcnt lgkmcnt(1)
	v_cvt_pk_bf16_f32 v88, v88, v89
	v_cvt_pk_bf16_f32 v89, v90, v91
	s_waitcnt lgkmcnt(0)
	v_cvt_pk_bf16_f32 v90, v92, v93
	v_lshlrev_b64 v[92:93], 10, v[128:129]
	v_cvt_pk_bf16_f32 v91, v94, v95
	v_lshl_add_u64 v[92:93], v[150:151], 0, v[92:93]
	global_store_dwordx4 v[92:93], v[88:91], off
	v_mov_b64_e32 v[114:115], v[82:83]
	s_cmp_eq_u32 s2, 64
	v_mov_b64_e32 v[90:91], v[70:71]
	v_mov_b64_e32 v[104:105], v[84:85]
	v_mov_b64_e32 v[88:89], v[68:69]
	v_mov_b64_e32 v[96:97], v[72:73]
	v_mov_b64_e32 v[108:109], v[76:77]
	v_mov_b64_e32 v[112:113], v[80:81]
	s_mov_b32 s15, s2
	s_cbranch_scc0 .LBB0_481
	s_setprio 0
	v_mov_b32_e32 v158, v222
	v_mov_b32_e32 v159, v223
	s_barrier
	s_branch .LBB0_395
